# v76 + ada GEMM: MFMAs of the never-read padding row blocks (tile rows 144..255 of the 132-row ada GEMM) removed from its K loop
# speedup vs baseline: 1.0016x; 1.0004x over previous
; #define PG8_STAGE(bufoff, gbase, voff) do { _Pragma("unroll") for (int _i = 0; _i < 2; ++_i) \
;         __builtin_amdgcn_global_load_lds((const unsigned*)((const char*)(gbase) + (voff)[_i]), (LAS unsigned*)(lds + (bufoff) + ldsw + _i * 8192), 16, 0, 0); } while (0)
; #define PG8_LDA(dst, b, h) do { _Pragma("unroll") for (int m = 0; m < 4; ++m) _Pragma("unroll") for (int k = 0; k < 2; ++k) dst[m][k] = *(const LAS bf16x8*)(lds + PG8_SA(b, h) + aoff + m * 2048 + k * 1024); } while (0)
; #define PG8_LDB(dst, b, h) do { _Pragma("unroll") for (int n = 0; n < 2; ++n) _Pragma("unroll") for (int k = 0; k < 2; ++k) dst[n][k] = *(const LAS bf16x8*)(lds + PG8_SB(b, h) + boff + n * 2048 + k * 1024); } while (0)
; #define PG8_WAIT_V(n) asm volatile("s_waitcnt vmcnt(" #n ")" ::: "memory")
; #define PG8_WAIT_L(n) asm volatile("s_waitcnt lgkmcnt(" #n ")" ::: "memory")
; #define PG8_BAR __builtin_amdgcn_s_barrier()
; #define PG8_SCHED __builtin_amdgcn_sched_barrier(0)
; template <class Epi, class S_t>
; __device__ __forceinline__ void gemm_phase(LAS unsigned char* lds, int lda, int ldb, const S_t& S, const Epi& E) {
;     ...
;             PG8_LDB(B0, 0, 0); PG8_SCHED; PG8_LDA(At, 0, 0); PG8_STAGE(PG8_SA(1, 1), a1 + hstepA, voffA);
;             PG8_WAIT_L(8); PG8_BAR; PG8_WAIT_L(0); PG8_MMA(0, 0, At, B0); PG8_BAR; PG8_SCHED;
;             PG8_LDB(B1, 0, 1); PG8_STAGE(PG8_SB(0, 0), b2, voffB);
;             PG8_BAR; PG8_WAIT_L(0); PG8_MMA(0, 1, At, B1); PG8_BAR;
;             PG8_LDA(At, 0, 1); PG8_STAGE(PG8_SA(0, 0), a2, voffA);
;             PG8_BAR; PG8_WAIT_L(0); PG8_MMA(1, 0, At, B0); PG8_BAR; PG8_SCHED;
;             PG8_STAGE(PG8_SB(0, 1), b2 + hstepB, voffB);
;             PG8_WAIT_V(6); PG8_BAR; PG8_MMA(1, 1, At, B1); PG8_BAR;
;             PG8_LDB(B0, 1, 0); PG8_SCHED; PG8_LDA(At, 1, 0); PG8_STAGE(PG8_SA(0, 1), a2 + hstepA, voffA);
;             PG8_WAIT_L(8); PG8_BAR; PG8_WAIT_L(0); PG8_MMA(0, 0, At, B0); PG8_BAR; PG8_SCHED;
;             PG8_LDB(B1, 1, 1); PG8_STAGE(PG8_SB(1, 0), b3, voffB);
;             PG8_BAR; PG8_WAIT_L(0); PG8_MMA(0, 1, At, B1); PG8_BAR;
;             PG8_LDA(At, 1, 1); PG8_STAGE(PG8_SA(1, 0), a3, voffA);
;             PG8_BAR; PG8_WAIT_L(0); PG8_MMA(1, 0, At, B0); PG8_BAR; PG8_SCHED;
;             PG8_STAGE(PG8_SB(1, 1), b3 + hstepB, voffB);
;             PG8_WAIT_V(6); PG8_BAR; PG8_MMA(1, 1, At, B1); PG8_BAR;
.LBB0_133:
	ds_read_b128 v[152:155], v175
	ds_read_b128 v[156:159], v175 offset:1024
	ds_read_b128 v[160:163], v175 offset:2048
	ds_read_b128 v[164:167], v175 offset:3072
	s_add_u32 s18, s16, 0xfff80080
	s_addc_u32 s19, s17, -1
	s_cmp_eq_u32 s9, 28
	s_cselect_b32 s21, s11, s19
	s_cselect_b32 s20, s10, s18
	s_cselect_b32 s19, s13, s1
	s_cselect_b32 s18, s12, s0
	s_add_i32 m0, s53, 0xc000
	ds_read_b128 v[186:189], v178
	ds_read_b128 v[190:193], v178 offset:1024
	ds_read_b128 v[194:197], v178 offset:2048
	ds_read_b128 v[198:201], v178 offset:3072
	ds_read_b128 v[202:205], v178 offset:4096
	ds_read_b128 v[206:209], v178 offset:5120
	ds_read_b128 v[214:217], v178 offset:6144
	ds_read_b128 v[218:221], v178 offset:7168
	global_load_lds_dwordx4 v148, s[16:17]
	s_add_i32 m0, s53, 0xe000
	s_nop 0
	global_load_lds_dwordx4 v150, s[16:17]
	s_waitcnt lgkmcnt(8)
	s_barrier
	s_waitcnt lgkmcnt(0)
	s_setprio 1
	v_mfma_f32_16x16x32_bf16 v[124:127], v[152:155], v[186:189], v[124:127]
	v_mfma_f32_16x16x32_bf16 v[92:95], v[160:163], v[186:189], v[92:95]
	v_mfma_f32_16x16x32_bf16 v[120:123], v[152:155], v[194:197], v[120:123]
	v_mfma_f32_16x16x32_bf16 v[88:91], v[160:163], v[194:197], v[88:91]
	v_mfma_f32_16x16x32_bf16 v[116:119], v[152:155], v[202:205], v[116:119]
	v_mfma_f32_16x16x32_bf16 v[84:87], v[160:163], v[202:205], v[84:87]
	v_mfma_f32_16x16x32_bf16 v[112:115], v[152:155], v[214:217], v[112:115]
	v_mfma_f32_16x16x32_bf16 v[80:83], v[160:163], v[214:217], v[80:83]
	v_mfma_f32_16x16x32_bf16 v[124:127], v[156:159], v[190:193], v[124:127]
	v_mfma_f32_16x16x32_bf16 v[92:95], v[164:167], v[190:193], v[92:95]
	v_mfma_f32_16x16x32_bf16 v[120:123], v[156:159], v[198:201], v[120:123]
	v_mfma_f32_16x16x32_bf16 v[88:91], v[164:167], v[198:201], v[88:91]
	v_mfma_f32_16x16x32_bf16 v[116:119], v[156:159], v[206:209], v[116:119]
	v_mfma_f32_16x16x32_bf16 v[84:87], v[164:167], v[206:209], v[84:87]
	v_mfma_f32_16x16x32_bf16 v[112:115], v[156:159], v[218:221], v[112:115]
	v_mfma_f32_16x16x32_bf16 v[80:83], v[164:167], v[218:221], v[80:83]
	s_setprio 0
	s_barrier
	s_add_i32 s33, s62, s43
	s_add_u32 s98, s18, s6
	s_addc_u32 s99, s19, s7
	s_mov_b32 m0, s33
	ds_read_b128 v[222:225], v179
	ds_read_b128 v[226:229], v179 offset:1024
	ds_read_b128 v[230:233], v179 offset:2048
	ds_read_b128 v[234:237], v179 offset:3072
	global_load_lds_dwordx4 v128, s[18:19]
	s_add_i32 m0, s33, 0x2000
	s_nop 0
	global_load_lds_dwordx4 v130, s[18:19]
	s_barrier
	s_waitcnt lgkmcnt(0)
	s_setprio 1
	v_mfma_f32_16x16x32_bf16 v[60:63], v[222:225], v[186:189], v[60:63]
	v_mfma_f32_16x16x32_bf16 v[28:31], v[230:233], v[186:189], v[28:31]
	v_mfma_f32_16x16x32_bf16 v[56:59], v[222:225], v[194:197], v[56:59]
	v_mfma_f32_16x16x32_bf16 v[24:27], v[230:233], v[194:197], v[24:27]
	v_mfma_f32_16x16x32_bf16 v[52:55], v[222:225], v[202:205], v[52:55]
	v_mfma_f32_16x16x32_bf16 v[20:23], v[230:233], v[202:205], v[20:23]
	v_mfma_f32_16x16x32_bf16 v[48:51], v[222:225], v[214:217], v[48:51]
	v_mfma_f32_16x16x32_bf16 v[16:19], v[230:233], v[214:217], v[16:19]
	v_mfma_f32_16x16x32_bf16 v[60:63], v[226:229], v[190:193], v[60:63]
	v_mfma_f32_16x16x32_bf16 v[28:31], v[234:237], v[190:193], v[28:31]
	v_mfma_f32_16x16x32_bf16 v[56:59], v[226:229], v[198:201], v[56:59]
	v_mfma_f32_16x16x32_bf16 v[24:27], v[234:237], v[198:201], v[24:27]
	v_mfma_f32_16x16x32_bf16 v[52:55], v[226:229], v[206:209], v[52:55]
	v_mfma_f32_16x16x32_bf16 v[20:23], v[234:237], v[206:209], v[20:23]
	v_mfma_f32_16x16x32_bf16 v[48:51], v[226:229], v[218:221], v[48:51]
	v_mfma_f32_16x16x32_bf16 v[16:19], v[234:237], v[218:221], v[16:19]
	s_setprio 0
	s_mov_b32 m0, s53
	s_add_u32 s100, s20, s6
	s_addc_u32 s101, s21, s7
	s_barrier
	ds_read_b128 v[186:189], v178 offset:16384
	ds_read_b128 v[190:193], v178 offset:17408
	ds_read_b128 v[194:197], v178 offset:18432
	ds_read_b128 v[198:201], v178 offset:19456
	ds_read_b128 v[202:205], v178 offset:20480
	ds_read_b128 v[206:209], v178 offset:21504
	ds_read_b128 v[214:217], v178 offset:22528
	ds_read_b128 v[218:221], v178 offset:23552
	global_load_lds_dwordx4 v128, s[20:21]
	s_mov_b32 m0, s54
	s_nop 0
	global_load_lds_dwordx4 v130, s[20:21]
	s_barrier
	s_waitcnt lgkmcnt(0)
	s_setprio 1
	v_mfma_f32_16x16x32_bf16 v[108:111], v[152:155], v[186:189], v[108:111]
	v_mfma_f32_16x16x32_bf16 v[76:79], v[160:163], v[186:189], v[76:79]
	v_mfma_f32_16x16x32_bf16 v[108:111], v[156:159], v[190:193], v[108:111]
	v_mfma_f32_16x16x32_bf16 v[76:79], v[164:167], v[190:193], v[76:79]
	s_setprio 0
	s_barrier
	s_add_u32 s66, s18, 0x80000
	s_addc_u32 s67, s19, 0
	s_add_i32 s33, s63, s43
	s_mov_b32 m0, s33
	s_nop 0
	global_load_lds_dwordx4 v128, s[66:67]
	s_add_i32 m0, s33, 0x2000
	s_nop 0
	global_load_lds_dwordx4 v130, s[66:67]
	s_waitcnt vmcnt(6)
	s_barrier
	s_setprio 1
	v_mfma_f32_16x16x32_bf16 v[44:47], v[222:225], v[186:189], v[44:47]
	v_mfma_f32_16x16x32_bf16 v[12:15], v[230:233], v[186:189], v[12:15]
	v_mfma_f32_16x16x32_bf16 v[44:47], v[226:229], v[190:193], v[44:47]
	v_mfma_f32_16x16x32_bf16 v[12:15], v[234:237], v[190:193], v[12:15]
	s_setprio 0
	s_add_i32 s33, 0, 0x18000
	v_add_u32_e32 v164, s33, v171
	s_barrier
	ds_read_b128 v[152:155], v164
	ds_read_b128 v[156:159], v164 offset:1024
	ds_read_b128 v[160:163], v164 offset:2048
	ds_read_b128 v[164:167], v164 offset:3072
	s_add_u32 s20, s20, 0x80000
	s_addc_u32 s21, s21, 0
	s_mov_b32 m0, s55
	ds_read_b128 v[186:189], v178 offset:32768
	ds_read_b128 v[190:193], v178 offset:33792
	ds_read_b128 v[194:197], v178 offset:34816
	ds_read_b128 v[198:201], v178 offset:35840
	ds_read_b128 v[202:205], v178 offset:36864
	ds_read_b128 v[206:209], v178 offset:37888
	ds_read_b128 v[214:217], v178 offset:38912
	ds_read_b128 v[218:221], v178 offset:39936
	global_load_lds_dwordx4 v128, s[20:21]
	s_mov_b32 m0, s56
	s_nop 0
	global_load_lds_dwordx4 v130, s[20:21]
	s_waitcnt lgkmcnt(8)
	s_barrier
; #define PG8_STAGE(bufoff, gbase, voff) do { _Pragma("unroll") for (int _i = 0; _i < 2; ++_i) \
;         __builtin_amdgcn_global_load_lds((const unsigned*)((const char*)(gbase) + (voff)[_i]), (LAS unsigned*)(lds + (bufoff) + ldsw + _i * 8192), 16, 0, 0); } while (0)
; #define PG8_LDA(dst, b, h) do { _Pragma("unroll") for (int m = 0; m < 4; ++m) _Pragma("unroll") for (int k = 0; k < 2; ++k) dst[m][k] = *(const LAS bf16x8*)(lds + PG8_SA(b, h) + aoff + m * 2048 + k * 1024); } while (0)
; #define PG8_WAIT_V(n) asm volatile("s_waitcnt vmcnt(" #n ")" ::: "memory")
; #define PG8_WAIT_L(n) asm volatile("s_waitcnt lgkmcnt(" #n ")" ::: "memory")
; template <class Epi, class S_t>
; __device__ __forceinline__ void gemm_phase(LAS unsigned char* lds, int lda, int ldb, const S_t& S, const Epi& E) {
;     ...
;             PG8_LDB(B0, 0, 0); PG8_SCHED; PG8_LDA(At, 0, 0); PG8_STAGE(PG8_SA(1, 1), a1 + hstepA, voffA);
;             PG8_WAIT_L(8); PG8_BAR; PG8_WAIT_L(0); PG8_MMA(0, 0, At, B0); PG8_BAR; PG8_SCHED;
;             PG8_LDB(B1, 0, 1); PG8_STAGE(PG8_SB(0, 0), b2, voffB);
;             PG8_BAR; PG8_WAIT_L(0); PG8_MMA(0, 1, At, B1); PG8_BAR;
;             PG8_LDA(At, 0, 1); PG8_STAGE(PG8_SA(0, 0), a2, voffA);
;             PG8_BAR; PG8_WAIT_L(0); PG8_MMA(1, 0, At, B0); PG8_BAR; PG8_SCHED;
;             PG8_STAGE(PG8_SB(0, 1), b2 + hstepB, voffB);
;             PG8_WAIT_V(6); PG8_BAR; PG8_MMA(1, 1, At, B1); PG8_BAR;
;             PG8_LDB(B0, 1, 0); PG8_SCHED; PG8_LDA(At, 1, 0); PG8_STAGE(PG8_SA(0, 1), a2 + hstepA, voffA);
;             PG8_WAIT_L(8); PG8_BAR; PG8_WAIT_L(0); PG8_MMA(0, 0, At, B0); PG8_BAR; PG8_SCHED;
;             PG8_LDB(B1, 1, 1); PG8_STAGE(PG8_SB(1, 0), b3, voffB);
;             PG8_BAR; PG8_WAIT_L(0); PG8_MMA(0, 1, At, B1); PG8_BAR;
;             PG8_LDA(At, 1, 1); PG8_STAGE(PG8_SA(1, 0), a3, voffA);
;             PG8_BAR; PG8_WAIT_L(0); PG8_MMA(1, 0, At, B0); PG8_BAR; PG8_SCHED;
;             PG8_STAGE(PG8_SB(1, 1), b3 + hstepB, voffB);
;             PG8_WAIT_V(6); PG8_BAR; PG8_MMA(1, 1, At, B1); PG8_BAR;
;     __device__ __forceinline__ void operator()(const f32x4 (&acc)[2][2][4][2], const Unit& u, int wr, int wc, int fr, int fq) const {
;         const int row0 = wr * 64 + fr, col0 = u.pn * BM + wc * 32 + 4 * fq, kind = u.pn >> 3;
;         const float* gm = kind == 2 ? g2 : kind == 4 ? g4 : kind == 5 ? g5 : g1;
	s_waitcnt lgkmcnt(0)
	s_setprio 1
	v_mfma_f32_16x16x32_bf16 v[124:127], v[152:155], v[186:189], v[124:127]
	v_mfma_f32_16x16x32_bf16 v[92:95], v[160:163], v[186:189], v[92:95]
	v_mfma_f32_16x16x32_bf16 v[120:123], v[152:155], v[194:197], v[120:123]
	v_mfma_f32_16x16x32_bf16 v[88:91], v[160:163], v[194:197], v[88:91]
	v_mfma_f32_16x16x32_bf16 v[116:119], v[152:155], v[202:205], v[116:119]
	v_mfma_f32_16x16x32_bf16 v[84:87], v[160:163], v[202:205], v[84:87]
	v_mfma_f32_16x16x32_bf16 v[112:115], v[152:155], v[214:217], v[112:115]
	v_mfma_f32_16x16x32_bf16 v[80:83], v[160:163], v[214:217], v[80:83]
	v_mfma_f32_16x16x32_bf16 v[124:127], v[156:159], v[190:193], v[124:127]
	v_mfma_f32_16x16x32_bf16 v[92:95], v[164:167], v[190:193], v[92:95]
	v_mfma_f32_16x16x32_bf16 v[120:123], v[156:159], v[198:201], v[120:123]
	v_mfma_f32_16x16x32_bf16 v[88:91], v[164:167], v[198:201], v[88:91]
	v_mfma_f32_16x16x32_bf16 v[116:119], v[156:159], v[206:209], v[116:119]
	v_mfma_f32_16x16x32_bf16 v[84:87], v[164:167], v[206:209], v[84:87]
	v_mfma_f32_16x16x32_bf16 v[112:115], v[156:159], v[218:221], v[112:115]
	v_mfma_f32_16x16x32_bf16 v[80:83], v[164:167], v[218:221], v[80:83]
	s_setprio 0
	s_barrier
	s_add_i32 s20, 0, 0x1c000
	s_add_i32 s21, s33, s43
	v_add_u32_e32 v170, s20, v171
	s_mov_b32 m0, s21
	ds_read_b128 v[222:225], v170
	ds_read_b128 v[226:229], v170 offset:1024
	ds_read_b128 v[230:233], v170 offset:2048
	ds_read_b128 v[234:237], v170 offset:3072
	global_load_lds_dwordx4 v128, s[98:99]
	s_add_i32 m0, s21, 0x2000
	s_nop 0
	global_load_lds_dwordx4 v130, s[98:99]
	s_barrier
	s_waitcnt lgkmcnt(0)
	s_setprio 1
	v_mfma_f32_16x16x32_bf16 v[60:63], v[222:225], v[186:189], v[60:63]
	v_mfma_f32_16x16x32_bf16 v[28:31], v[230:233], v[186:189], v[28:31]
	v_mfma_f32_16x16x32_bf16 v[56:59], v[222:225], v[194:197], v[56:59]
	v_mfma_f32_16x16x32_bf16 v[24:27], v[230:233], v[194:197], v[24:27]
	v_mfma_f32_16x16x32_bf16 v[52:55], v[222:225], v[202:205], v[52:55]
	v_mfma_f32_16x16x32_bf16 v[20:23], v[230:233], v[202:205], v[20:23]
	v_mfma_f32_16x16x32_bf16 v[48:51], v[222:225], v[214:217], v[48:51]
	v_mfma_f32_16x16x32_bf16 v[16:19], v[230:233], v[214:217], v[16:19]
	v_mfma_f32_16x16x32_bf16 v[60:63], v[226:229], v[190:193], v[60:63]
	v_mfma_f32_16x16x32_bf16 v[28:31], v[234:237], v[190:193], v[28:31]
	v_mfma_f32_16x16x32_bf16 v[56:59], v[226:229], v[198:201], v[56:59]
	v_mfma_f32_16x16x32_bf16 v[24:27], v[234:237], v[198:201], v[24:27]
	v_mfma_f32_16x16x32_bf16 v[52:55], v[226:229], v[206:209], v[52:55]
	v_mfma_f32_16x16x32_bf16 v[20:23], v[234:237], v[206:209], v[20:23]
	v_mfma_f32_16x16x32_bf16 v[48:51], v[226:229], v[218:221], v[48:51]
	v_mfma_f32_16x16x32_bf16 v[16:19], v[234:237], v[218:221], v[16:19]
	s_setprio 0
	s_mov_b32 m0, s58
	s_barrier
	ds_read_b128 v[186:189], v178 offset:49152
	ds_read_b128 v[190:193], v178 offset:50176
	ds_read_b128 v[194:197], v178 offset:51200
	ds_read_b128 v[198:201], v178 offset:52224
	ds_read_b128 v[202:205], v178 offset:53248
	ds_read_b128 v[206:209], v178 offset:54272
	ds_read_b128 v[214:217], v178 offset:55296
	ds_read_b128 v[218:221], v178 offset:56320
	global_load_lds_dwordx4 v128, s[100:101]
	s_mov_b32 m0, s59
	s_nop 0
	global_load_lds_dwordx4 v130, s[100:101]
	s_barrier
	s_waitcnt lgkmcnt(0)
	s_setprio 1
	v_mfma_f32_16x16x32_bf16 v[108:111], v[152:155], v[186:189], v[108:111]
	v_mfma_f32_16x16x32_bf16 v[76:79], v[160:163], v[186:189], v[76:79]
	v_mfma_f32_16x16x32_bf16 v[108:111], v[156:159], v[190:193], v[108:111]
	v_mfma_f32_16x16x32_bf16 v[76:79], v[164:167], v[190:193], v[76:79]
	s_setprio 0
	s_barrier
	s_add_u32 s18, s18, 0x80080
	s_addc_u32 s19, s19, 0
	s_add_i32 s20, s20, s43
	s_mov_b32 m0, s20
	s_nop 0
	global_load_lds_dwordx4 v128, s[18:19]
	s_add_i32 m0, s20, 0x2000
	s_nop 0
	global_load_lds_dwordx4 v130, s[18:19]
	s_waitcnt vmcnt(6)
	s_barrier
	s_setprio 1
	v_mfma_f32_16x16x32_bf16 v[44:47], v[222:225], v[186:189], v[44:47]
	v_mfma_f32_16x16x32_bf16 v[12:15], v[230:233], v[186:189], v[12:15]
	v_mfma_f32_16x16x32_bf16 v[44:47], v[226:229], v[190:193], v[44:47]
	v_mfma_f32_16x16x32_bf16 v[12:15], v[234:237], v[190:193], v[12:15]
	s_setprio 0
	s_add_i32 s9, s9, 2
	s_add_u32 s16, s16, 0x100
	s_addc_u32 s17, s17, 0
	s_add_u32 s0, s0, 0x100
	s_addc_u32 s1, s1, 0
	s_cmp_gt_u32 s9, 29
	s_barrier
	s_cbranch_scc0 .LBB0_133
	s_ashr_i32 s9, s64, 3
	s_cmp_lt_i32 s9, 4
	s_cbranch_scc1 .LBB0_138
	v_readlane_b32 s68, v254, 17
	v_readlane_b32 s76, v254, 25
	v_readlane_b32 s77, v254, 26
	s_cmp_gt_i32 s9, 4
	s_mov_b64 s[18:19], 0
	s_mov_b64 s[16:17], s[76:77]
	s_mov_b64 s[0:1], 0
	v_readlane_b32 s69, v254, 18
	v_readlane_b32 s70, v254, 19
	v_readlane_b32 s71, v254, 20
	v_readlane_b32 s72, v254, 21
	v_readlane_b32 s73, v254, 22
	v_readlane_b32 s74, v254, 23
	v_readlane_b32 s75, v254, 24
	v_readlane_b32 s78, v254, 27
	v_readlane_b32 s79, v254, 28
	v_readlane_b32 s80, v254, 29
	v_readlane_b32 s81, v254, 30
	v_readlane_b32 s82, v254, 31
	v_readlane_b32 s83, v254, 32
	s_cbranch_scc0 .LBB0_139
	s_cmp_eq_u32 s9, 5
	s_mov_b64 s[0:1], -1
	s_cbranch_scc0 .LBB0_139
	v_readlane_b32 s68, v254, 17
	v_readlane_b32 s78, v254, 27
	v_readlane_b32 s79, v254, 28
	s_mov_b64 s[0:1], 0
	v_readlane_b32 s69, v254, 18
	v_readlane_b32 s70, v254, 19
	v_readlane_b32 s71, v254, 20
	v_readlane_b32 s72, v254, 21
	v_readlane_b32 s73, v254, 22
	v_readlane_b32 s74, v254, 23
	v_readlane_b32 s75, v254, 24
	v_readlane_b32 s76, v254, 25
	v_readlane_b32 s77, v254, 26
	v_readlane_b32 s80, v254, 29
	v_readlane_b32 s81, v254, 30
	v_readlane_b32 s82, v254, 31
	v_readlane_b32 s83, v254, 32
	s_mov_b64 s[16:17], s[78:79]
	s_branch .LBB0_139
